# phase-1 tile epilogue rewritten by hand: one branch on the column segment, running offsets, immediate store offsets
# speedup vs baseline: 1.0074x; 1.0074x over previous
.LBB0_237:
	s_lshl_b32 s14, s13, 8
	s_add_i32 s14, s14, s55
	s_lshl_b32 s10, s12, 8
	v_or_b32_e32 v146, s14, v155
	v_or_b32_e32 v144, s10, v159
	s_ashr_i32 s6, s12, 1
	v_mov_b32_e32 v153, 0
	s_cmp_eq_u32 s6, 0
	s_cbranch_scc1 .Lp1e_q
	s_cmp_eq_u32 s6, 3
	s_cbranch_scc1 .Lp1e_u
	s_mov_b32 s72, 0x4100000
	s_cmp_eq_u32 s6, 2
	s_cselect_b32 s72, 0x6100000, s72
	v_mul_u32_u24_e32 v134, 0xc00, v146
	v_lshl_add_u32 v134, v144, 1, v134
	v_and_b32_e32 v152, 0x1ff, v144
	v_lshlrev_b32_e32 v152, 2, v152
	v_lshl_add_u32 v152, v146, 11, v152
	v_add_u32_e32 v152, s72, v152
	v_lshl_add_u64 v[148:149], s[94:95], 0, v[134:135]
	v_lshl_add_u64 v[150:151], s[84:85], 0, v[152:153]
	global_store_dwordx4 v[150:151], v[126:129], off nt
	global_store_dwordx4 v[150:151], v[122:125], off offset:64 nt
	global_store_dwordx4 v[150:151], v[118:121], off offset:512 nt
	global_store_dwordx4 v[150:151], v[114:117], off offset:576 nt
	v_cvt_pk_bf16_f32 v126, v126, v127
	v_cvt_pk_bf16_f32 v127, v128, v129
	v_cvt_pk_bf16_f32 v122, v122, v123
	v_cvt_pk_bf16_f32 v123, v124, v125
	v_cvt_pk_bf16_f32 v118, v118, v119
	v_cvt_pk_bf16_f32 v119, v120, v121
	v_cvt_pk_bf16_f32 v114, v114, v115
	v_cvt_pk_bf16_f32 v115, v116, v117
	global_store_dwordx2 v[148:149], v[126:127], off
	global_store_dwordx2 v[148:149], v[122:123], off offset:32
	global_store_dwordx2 v[148:149], v[118:119], off offset:256
	global_store_dwordx2 v[148:149], v[114:115], off offset:288
	v_add_u32_e32 v134, 0xc000, v134
	v_add_u32_e32 v152, 0x8000, v152
	v_lshl_add_u64 v[148:149], s[94:95], 0, v[134:135]
	v_lshl_add_u64 v[150:151], s[84:85], 0, v[152:153]
	global_store_dwordx4 v[150:151], v[110:113], off nt
	global_store_dwordx4 v[150:151], v[106:109], off offset:64 nt
	global_store_dwordx4 v[150:151], v[102:105], off offset:512 nt
	global_store_dwordx4 v[150:151], v[98:101], off offset:576 nt
	v_cvt_pk_bf16_f32 v110, v110, v111
	v_cvt_pk_bf16_f32 v111, v112, v113
	v_cvt_pk_bf16_f32 v106, v106, v107
	v_cvt_pk_bf16_f32 v107, v108, v109
	v_cvt_pk_bf16_f32 v102, v102, v103
	v_cvt_pk_bf16_f32 v103, v104, v105
	v_cvt_pk_bf16_f32 v98, v98, v99
	v_cvt_pk_bf16_f32 v99, v100, v101
	global_store_dwordx2 v[148:149], v[110:111], off
	global_store_dwordx2 v[148:149], v[106:107], off offset:32
	global_store_dwordx2 v[148:149], v[102:103], off offset:256
	global_store_dwordx2 v[148:149], v[98:99], off offset:288
	v_add_u32_e32 v134, 0xc000, v134
	v_add_u32_e32 v152, 0x8000, v152
	v_lshl_add_u64 v[148:149], s[94:95], 0, v[134:135]
	v_lshl_add_u64 v[150:151], s[84:85], 0, v[152:153]
	global_store_dwordx4 v[150:151], v[94:97], off nt
	global_store_dwordx4 v[150:151], v[90:93], off offset:64 nt
	global_store_dwordx4 v[150:151], v[86:89], off offset:512 nt
	global_store_dwordx4 v[150:151], v[82:85], off offset:576 nt
	v_cvt_pk_bf16_f32 v94, v94, v95
	v_cvt_pk_bf16_f32 v95, v96, v97
	v_cvt_pk_bf16_f32 v90, v90, v91
	v_cvt_pk_bf16_f32 v91, v92, v93
	v_cvt_pk_bf16_f32 v86, v86, v87
	v_cvt_pk_bf16_f32 v87, v88, v89
	v_cvt_pk_bf16_f32 v82, v82, v83
	v_cvt_pk_bf16_f32 v83, v84, v85
	global_store_dwordx2 v[148:149], v[94:95], off
	global_store_dwordx2 v[148:149], v[90:91], off offset:32
	global_store_dwordx2 v[148:149], v[86:87], off offset:256
	global_store_dwordx2 v[148:149], v[82:83], off offset:288
	v_add_u32_e32 v134, 0xc000, v134
	v_add_u32_e32 v152, 0x8000, v152
	v_lshl_add_u64 v[148:149], s[94:95], 0, v[134:135]
	v_lshl_add_u64 v[150:151], s[84:85], 0, v[152:153]
	global_store_dwordx4 v[150:151], v[78:81], off nt
	global_store_dwordx4 v[150:151], v[74:77], off offset:64 nt
	global_store_dwordx4 v[150:151], v[70:73], off offset:512 nt
	global_store_dwordx4 v[150:151], v[66:69], off offset:576 nt
	v_cvt_pk_bf16_f32 v78, v78, v79
	v_cvt_pk_bf16_f32 v79, v80, v81
	v_cvt_pk_bf16_f32 v74, v74, v75
	v_cvt_pk_bf16_f32 v75, v76, v77
	v_cvt_pk_bf16_f32 v70, v70, v71
	v_cvt_pk_bf16_f32 v71, v72, v73
	v_cvt_pk_bf16_f32 v66, v66, v67
	v_cvt_pk_bf16_f32 v67, v68, v69
	global_store_dwordx2 v[148:149], v[78:79], off
	global_store_dwordx2 v[148:149], v[74:75], off offset:32
	global_store_dwordx2 v[148:149], v[70:71], off offset:256
	global_store_dwordx2 v[148:149], v[66:67], off offset:288
	v_add_u32_e32 v134, 0x3c000, v134
	v_add_u32_e32 v152, 0x28000, v152
	v_lshl_add_u64 v[148:149], s[94:95], 0, v[134:135]
	v_lshl_add_u64 v[150:151], s[84:85], 0, v[152:153]
	global_store_dwordx4 v[150:151], v[62:65], off nt
	global_store_dwordx4 v[150:151], v[58:61], off offset:64 nt
	global_store_dwordx4 v[150:151], v[54:57], off offset:512 nt
	global_store_dwordx4 v[150:151], v[50:53], off offset:576 nt
	v_cvt_pk_bf16_f32 v62, v62, v63
	v_cvt_pk_bf16_f32 v63, v64, v65
	v_cvt_pk_bf16_f32 v58, v58, v59
	v_cvt_pk_bf16_f32 v59, v60, v61
	v_cvt_pk_bf16_f32 v54, v54, v55
	v_cvt_pk_bf16_f32 v55, v56, v57
	v_cvt_pk_bf16_f32 v50, v50, v51
	v_cvt_pk_bf16_f32 v51, v52, v53
	global_store_dwordx2 v[148:149], v[62:63], off
	global_store_dwordx2 v[148:149], v[58:59], off offset:32
	global_store_dwordx2 v[148:149], v[54:55], off offset:256
	global_store_dwordx2 v[148:149], v[50:51], off offset:288
	v_add_u32_e32 v134, 0xc000, v134
	v_add_u32_e32 v152, 0x8000, v152
	v_lshl_add_u64 v[148:149], s[94:95], 0, v[134:135]
	v_lshl_add_u64 v[150:151], s[84:85], 0, v[152:153]
	global_store_dwordx4 v[150:151], v[46:49], off nt
	global_store_dwordx4 v[150:151], v[42:45], off offset:64 nt
	global_store_dwordx4 v[150:151], v[38:41], off offset:512 nt
	global_store_dwordx4 v[150:151], v[34:37], off offset:576 nt
	v_cvt_pk_bf16_f32 v46, v46, v47
	v_cvt_pk_bf16_f32 v47, v48, v49
	v_cvt_pk_bf16_f32 v42, v42, v43
	v_cvt_pk_bf16_f32 v43, v44, v45
	v_cvt_pk_bf16_f32 v38, v38, v39
	v_cvt_pk_bf16_f32 v39, v40, v41
	v_cvt_pk_bf16_f32 v34, v34, v35
	v_cvt_pk_bf16_f32 v35, v36, v37
	global_store_dwordx2 v[148:149], v[46:47], off
	global_store_dwordx2 v[148:149], v[42:43], off offset:32
	global_store_dwordx2 v[148:149], v[38:39], off offset:256
	global_store_dwordx2 v[148:149], v[34:35], off offset:288
	v_add_u32_e32 v134, 0xc000, v134
	v_add_u32_e32 v152, 0x8000, v152
	v_lshl_add_u64 v[148:149], s[94:95], 0, v[134:135]
	v_lshl_add_u64 v[150:151], s[84:85], 0, v[152:153]
	global_store_dwordx4 v[150:151], v[30:33], off nt
	global_store_dwordx4 v[150:151], v[26:29], off offset:64 nt
	global_store_dwordx4 v[150:151], v[22:25], off offset:512 nt
	global_store_dwordx4 v[150:151], v[18:21], off offset:576 nt
	v_cvt_pk_bf16_f32 v30, v30, v31
	v_cvt_pk_bf16_f32 v31, v32, v33
	v_cvt_pk_bf16_f32 v26, v26, v27
	v_cvt_pk_bf16_f32 v27, v28, v29
	v_cvt_pk_bf16_f32 v22, v22, v23
	v_cvt_pk_bf16_f32 v23, v24, v25
	v_cvt_pk_bf16_f32 v18, v18, v19
	v_cvt_pk_bf16_f32 v19, v20, v21
	global_store_dwordx2 v[148:149], v[30:31], off
	global_store_dwordx2 v[148:149], v[26:27], off offset:32
	global_store_dwordx2 v[148:149], v[22:23], off offset:256
	global_store_dwordx2 v[148:149], v[18:19], off offset:288
	v_add_u32_e32 v134, 0xc000, v134
	v_add_u32_e32 v152, 0x8000, v152
	v_lshl_add_u64 v[148:149], s[94:95], 0, v[134:135]
	v_lshl_add_u64 v[150:151], s[84:85], 0, v[152:153]
	global_store_dwordx4 v[150:151], v[14:17], off nt
	global_store_dwordx4 v[150:151], v[10:13], off offset:64 nt
	global_store_dwordx4 v[150:151], v[6:9], off offset:512 nt
	global_store_dwordx4 v[150:151], v[2:5], off offset:576 nt
	v_cvt_pk_bf16_f32 v14, v14, v15
	v_cvt_pk_bf16_f32 v15, v16, v17
	v_cvt_pk_bf16_f32 v10, v10, v11
	v_cvt_pk_bf16_f32 v11, v12, v13
	v_cvt_pk_bf16_f32 v6, v6, v7
	v_cvt_pk_bf16_f32 v7, v8, v9
	v_cvt_pk_bf16_f32 v2, v2, v3
	v_cvt_pk_bf16_f32 v3, v4, v5
	global_store_dwordx2 v[148:149], v[14:15], off
	global_store_dwordx2 v[148:149], v[10:11], off offset:32
	global_store_dwordx2 v[148:149], v[6:7], off offset:256
	global_store_dwordx2 v[148:149], v[2:3], off offset:288
	s_branch .LBB0_223
.Lp1e_q:
	v_mul_u32_u24_e32 v134, 0xc00, v146
	v_lshl_add_u32 v134, v144, 1, v134
	v_lshl_add_u64 v[148:149], s[94:95], 0, v[134:135]
	v_pk_mul_f32 v[126:127], v[126:127], s[54:55] op_sel_hi:[1,0]
	v_pk_mul_f32 v[128:129], v[128:129], s[54:55] op_sel_hi:[1,0]
	v_pk_mul_f32 v[122:123], v[122:123], s[54:55] op_sel_hi:[1,0]
	v_pk_mul_f32 v[124:125], v[124:125], s[54:55] op_sel_hi:[1,0]
	v_pk_mul_f32 v[118:119], v[118:119], s[54:55] op_sel_hi:[1,0]
	v_pk_mul_f32 v[120:121], v[120:121], s[54:55] op_sel_hi:[1,0]
	v_pk_mul_f32 v[114:115], v[114:115], s[54:55] op_sel_hi:[1,0]
	v_pk_mul_f32 v[116:117], v[116:117], s[54:55] op_sel_hi:[1,0]
	v_cvt_pk_bf16_f32 v126, v126, v127
	v_cvt_pk_bf16_f32 v127, v128, v129
	v_cvt_pk_bf16_f32 v122, v122, v123
	v_cvt_pk_bf16_f32 v123, v124, v125
	v_cvt_pk_bf16_f32 v118, v118, v119
	v_cvt_pk_bf16_f32 v119, v120, v121
	v_cvt_pk_bf16_f32 v114, v114, v115
	v_cvt_pk_bf16_f32 v115, v116, v117
	global_store_dwordx2 v[148:149], v[126:127], off
	global_store_dwordx2 v[148:149], v[122:123], off offset:32
	global_store_dwordx2 v[148:149], v[118:119], off offset:256
	global_store_dwordx2 v[148:149], v[114:115], off offset:288
	v_add_u32_e32 v134, 0xc000, v134
	v_lshl_add_u64 v[148:149], s[94:95], 0, v[134:135]
	v_pk_mul_f32 v[110:111], v[110:111], s[54:55] op_sel_hi:[1,0]
	v_pk_mul_f32 v[112:113], v[112:113], s[54:55] op_sel_hi:[1,0]
	v_pk_mul_f32 v[106:107], v[106:107], s[54:55] op_sel_hi:[1,0]
	v_pk_mul_f32 v[108:109], v[108:109], s[54:55] op_sel_hi:[1,0]
	v_pk_mul_f32 v[102:103], v[102:103], s[54:55] op_sel_hi:[1,0]
	v_pk_mul_f32 v[104:105], v[104:105], s[54:55] op_sel_hi:[1,0]
	v_pk_mul_f32 v[98:99], v[98:99], s[54:55] op_sel_hi:[1,0]
	v_pk_mul_f32 v[100:101], v[100:101], s[54:55] op_sel_hi:[1,0]
	v_cvt_pk_bf16_f32 v110, v110, v111
	v_cvt_pk_bf16_f32 v111, v112, v113
	v_cvt_pk_bf16_f32 v106, v106, v107
	v_cvt_pk_bf16_f32 v107, v108, v109
	v_cvt_pk_bf16_f32 v102, v102, v103
	v_cvt_pk_bf16_f32 v103, v104, v105
	v_cvt_pk_bf16_f32 v98, v98, v99
	v_cvt_pk_bf16_f32 v99, v100, v101
	global_store_dwordx2 v[148:149], v[110:111], off
	global_store_dwordx2 v[148:149], v[106:107], off offset:32
	global_store_dwordx2 v[148:149], v[102:103], off offset:256
	global_store_dwordx2 v[148:149], v[98:99], off offset:288
	v_add_u32_e32 v134, 0xc000, v134
	v_lshl_add_u64 v[148:149], s[94:95], 0, v[134:135]
	v_pk_mul_f32 v[94:95], v[94:95], s[54:55] op_sel_hi:[1,0]
	v_pk_mul_f32 v[96:97], v[96:97], s[54:55] op_sel_hi:[1,0]
	v_pk_mul_f32 v[90:91], v[90:91], s[54:55] op_sel_hi:[1,0]
	v_pk_mul_f32 v[92:93], v[92:93], s[54:55] op_sel_hi:[1,0]
	v_pk_mul_f32 v[86:87], v[86:87], s[54:55] op_sel_hi:[1,0]
	v_pk_mul_f32 v[88:89], v[88:89], s[54:55] op_sel_hi:[1,0]
	v_pk_mul_f32 v[82:83], v[82:83], s[54:55] op_sel_hi:[1,0]
	v_pk_mul_f32 v[84:85], v[84:85], s[54:55] op_sel_hi:[1,0]
	v_cvt_pk_bf16_f32 v94, v94, v95
	v_cvt_pk_bf16_f32 v95, v96, v97
	v_cvt_pk_bf16_f32 v90, v90, v91
	v_cvt_pk_bf16_f32 v91, v92, v93
	v_cvt_pk_bf16_f32 v86, v86, v87
	v_cvt_pk_bf16_f32 v87, v88, v89
	v_cvt_pk_bf16_f32 v82, v82, v83
	v_cvt_pk_bf16_f32 v83, v84, v85
	global_store_dwordx2 v[148:149], v[94:95], off
	global_store_dwordx2 v[148:149], v[90:91], off offset:32
	global_store_dwordx2 v[148:149], v[86:87], off offset:256
	global_store_dwordx2 v[148:149], v[82:83], off offset:288
	v_add_u32_e32 v134, 0xc000, v134
	v_lshl_add_u64 v[148:149], s[94:95], 0, v[134:135]
	v_pk_mul_f32 v[78:79], v[78:79], s[54:55] op_sel_hi:[1,0]
	v_pk_mul_f32 v[80:81], v[80:81], s[54:55] op_sel_hi:[1,0]
	v_pk_mul_f32 v[74:75], v[74:75], s[54:55] op_sel_hi:[1,0]
	v_pk_mul_f32 v[76:77], v[76:77], s[54:55] op_sel_hi:[1,0]
	v_pk_mul_f32 v[70:71], v[70:71], s[54:55] op_sel_hi:[1,0]
	v_pk_mul_f32 v[72:73], v[72:73], s[54:55] op_sel_hi:[1,0]
	v_pk_mul_f32 v[66:67], v[66:67], s[54:55] op_sel_hi:[1,0]
	v_pk_mul_f32 v[68:69], v[68:69], s[54:55] op_sel_hi:[1,0]
	v_cvt_pk_bf16_f32 v78, v78, v79
	v_cvt_pk_bf16_f32 v79, v80, v81
	v_cvt_pk_bf16_f32 v74, v74, v75
	v_cvt_pk_bf16_f32 v75, v76, v77
	v_cvt_pk_bf16_f32 v70, v70, v71
	v_cvt_pk_bf16_f32 v71, v72, v73
	v_cvt_pk_bf16_f32 v66, v66, v67
	v_cvt_pk_bf16_f32 v67, v68, v69
	global_store_dwordx2 v[148:149], v[78:79], off
	global_store_dwordx2 v[148:149], v[74:75], off offset:32
	global_store_dwordx2 v[148:149], v[70:71], off offset:256
	global_store_dwordx2 v[148:149], v[66:67], off offset:288
	v_add_u32_e32 v134, 0x3c000, v134
	v_lshl_add_u64 v[148:149], s[94:95], 0, v[134:135]
	v_pk_mul_f32 v[62:63], v[62:63], s[54:55] op_sel_hi:[1,0]
	v_pk_mul_f32 v[64:65], v[64:65], s[54:55] op_sel_hi:[1,0]
	v_pk_mul_f32 v[58:59], v[58:59], s[54:55] op_sel_hi:[1,0]
	v_pk_mul_f32 v[60:61], v[60:61], s[54:55] op_sel_hi:[1,0]
	v_pk_mul_f32 v[54:55], v[54:55], s[54:55] op_sel_hi:[1,0]
	v_pk_mul_f32 v[56:57], v[56:57], s[54:55] op_sel_hi:[1,0]
	v_pk_mul_f32 v[50:51], v[50:51], s[54:55] op_sel_hi:[1,0]
	v_pk_mul_f32 v[52:53], v[52:53], s[54:55] op_sel_hi:[1,0]
	v_cvt_pk_bf16_f32 v62, v62, v63
	v_cvt_pk_bf16_f32 v63, v64, v65
	v_cvt_pk_bf16_f32 v58, v58, v59
	v_cvt_pk_bf16_f32 v59, v60, v61
	v_cvt_pk_bf16_f32 v54, v54, v55
	v_cvt_pk_bf16_f32 v55, v56, v57
	v_cvt_pk_bf16_f32 v50, v50, v51
	v_cvt_pk_bf16_f32 v51, v52, v53
	global_store_dwordx2 v[148:149], v[62:63], off
	global_store_dwordx2 v[148:149], v[58:59], off offset:32
	global_store_dwordx2 v[148:149], v[54:55], off offset:256
	global_store_dwordx2 v[148:149], v[50:51], off offset:288
	v_add_u32_e32 v134, 0xc000, v134
	v_lshl_add_u64 v[148:149], s[94:95], 0, v[134:135]
	v_pk_mul_f32 v[46:47], v[46:47], s[54:55] op_sel_hi:[1,0]
	v_pk_mul_f32 v[48:49], v[48:49], s[54:55] op_sel_hi:[1,0]
	v_pk_mul_f32 v[42:43], v[42:43], s[54:55] op_sel_hi:[1,0]
	v_pk_mul_f32 v[44:45], v[44:45], s[54:55] op_sel_hi:[1,0]
	v_pk_mul_f32 v[38:39], v[38:39], s[54:55] op_sel_hi:[1,0]
	v_pk_mul_f32 v[40:41], v[40:41], s[54:55] op_sel_hi:[1,0]
	v_pk_mul_f32 v[34:35], v[34:35], s[54:55] op_sel_hi:[1,0]
	v_pk_mul_f32 v[36:37], v[36:37], s[54:55] op_sel_hi:[1,0]
	v_cvt_pk_bf16_f32 v46, v46, v47
	v_cvt_pk_bf16_f32 v47, v48, v49
	v_cvt_pk_bf16_f32 v42, v42, v43
	v_cvt_pk_bf16_f32 v43, v44, v45
	v_cvt_pk_bf16_f32 v38, v38, v39
	v_cvt_pk_bf16_f32 v39, v40, v41
	v_cvt_pk_bf16_f32 v34, v34, v35
	v_cvt_pk_bf16_f32 v35, v36, v37
	global_store_dwordx2 v[148:149], v[46:47], off
	global_store_dwordx2 v[148:149], v[42:43], off offset:32
	global_store_dwordx2 v[148:149], v[38:39], off offset:256
	global_store_dwordx2 v[148:149], v[34:35], off offset:288
	v_add_u32_e32 v134, 0xc000, v134
	v_lshl_add_u64 v[148:149], s[94:95], 0, v[134:135]
	v_pk_mul_f32 v[30:31], v[30:31], s[54:55] op_sel_hi:[1,0]
	v_pk_mul_f32 v[32:33], v[32:33], s[54:55] op_sel_hi:[1,0]
	v_pk_mul_f32 v[26:27], v[26:27], s[54:55] op_sel_hi:[1,0]
	v_pk_mul_f32 v[28:29], v[28:29], s[54:55] op_sel_hi:[1,0]
	v_pk_mul_f32 v[22:23], v[22:23], s[54:55] op_sel_hi:[1,0]
	v_pk_mul_f32 v[24:25], v[24:25], s[54:55] op_sel_hi:[1,0]
	v_pk_mul_f32 v[18:19], v[18:19], s[54:55] op_sel_hi:[1,0]
	v_pk_mul_f32 v[20:21], v[20:21], s[54:55] op_sel_hi:[1,0]
	v_cvt_pk_bf16_f32 v30, v30, v31
	v_cvt_pk_bf16_f32 v31, v32, v33
	v_cvt_pk_bf16_f32 v26, v26, v27
	v_cvt_pk_bf16_f32 v27, v28, v29
	v_cvt_pk_bf16_f32 v22, v22, v23
	v_cvt_pk_bf16_f32 v23, v24, v25
	v_cvt_pk_bf16_f32 v18, v18, v19
	v_cvt_pk_bf16_f32 v19, v20, v21
	global_store_dwordx2 v[148:149], v[30:31], off
	global_store_dwordx2 v[148:149], v[26:27], off offset:32
	global_store_dwordx2 v[148:149], v[22:23], off offset:256
	global_store_dwordx2 v[148:149], v[18:19], off offset:288
	v_add_u32_e32 v134, 0xc000, v134
	v_lshl_add_u64 v[148:149], s[94:95], 0, v[134:135]
	v_pk_mul_f32 v[14:15], v[14:15], s[54:55] op_sel_hi:[1,0]
	v_pk_mul_f32 v[16:17], v[16:17], s[54:55] op_sel_hi:[1,0]
	v_pk_mul_f32 v[10:11], v[10:11], s[54:55] op_sel_hi:[1,0]
	v_pk_mul_f32 v[12:13], v[12:13], s[54:55] op_sel_hi:[1,0]
	v_pk_mul_f32 v[6:7], v[6:7], s[54:55] op_sel_hi:[1,0]
	v_pk_mul_f32 v[8:9], v[8:9], s[54:55] op_sel_hi:[1,0]
	v_pk_mul_f32 v[2:3], v[2:3], s[54:55] op_sel_hi:[1,0]
	v_pk_mul_f32 v[4:5], v[4:5], s[54:55] op_sel_hi:[1,0]
	v_cvt_pk_bf16_f32 v14, v14, v15
	v_cvt_pk_bf16_f32 v15, v16, v17
	v_cvt_pk_bf16_f32 v10, v10, v11
	v_cvt_pk_bf16_f32 v11, v12, v13
	v_cvt_pk_bf16_f32 v6, v6, v7
	v_cvt_pk_bf16_f32 v7, v8, v9
	v_cvt_pk_bf16_f32 v2, v2, v3
	v_cvt_pk_bf16_f32 v3, v4, v5
	global_store_dwordx2 v[148:149], v[14:15], off
	global_store_dwordx2 v[148:149], v[10:11], off offset:32
	global_store_dwordx2 v[148:149], v[6:7], off offset:256
	global_store_dwordx2 v[148:149], v[2:3], off offset:288
	s_branch .LBB0_223
.Lp1e_u:
	v_and_b32_e32 v134, 0x1ff, v144
	v_lshlrev_b32_e32 v147, 2, v134
	v_lshlrev_b32_e32 v134, 1, v134
	v_lshl_add_u32 v134, v146, 10, v134
	v_lshl_add_u64 v[148:149], s[44:45], 0, v[134:135]
	v_cvt_pk_bf16_f32 v126, v126, v127
	v_cvt_pk_bf16_f32 v127, v128, v129
	v_cvt_pk_bf16_f32 v122, v122, v123
	v_cvt_pk_bf16_f32 v123, v124, v125
	v_cvt_pk_bf16_f32 v118, v118, v119
	v_cvt_pk_bf16_f32 v119, v120, v121
	v_cvt_pk_bf16_f32 v114, v114, v115
	v_cvt_pk_bf16_f32 v115, v116, v117
	global_store_dwordx2 v[148:149], v[126:127], off
	global_store_dwordx2 v[148:149], v[122:123], off offset:32
	global_store_dwordx2 v[148:149], v[118:119], off offset:256
	global_store_dwordx2 v[148:149], v[114:115], off offset:288
	v_add_u32_e32 v134, 0x4000, v134
	v_lshl_add_u64 v[148:149], s[44:45], 0, v[134:135]
	v_cvt_pk_bf16_f32 v110, v110, v111
	v_cvt_pk_bf16_f32 v111, v112, v113
	v_cvt_pk_bf16_f32 v106, v106, v107
	v_cvt_pk_bf16_f32 v107, v108, v109
	v_cvt_pk_bf16_f32 v102, v102, v103
	v_cvt_pk_bf16_f32 v103, v104, v105
	v_cvt_pk_bf16_f32 v98, v98, v99
	v_cvt_pk_bf16_f32 v99, v100, v101
	global_store_dwordx2 v[148:149], v[110:111], off
	global_store_dwordx2 v[148:149], v[106:107], off offset:32
	global_store_dwordx2 v[148:149], v[102:103], off offset:256
	global_store_dwordx2 v[148:149], v[98:99], off offset:288
	v_add_u32_e32 v134, 0x4000, v134
	v_lshl_add_u64 v[148:149], s[44:45], 0, v[134:135]
	v_cvt_pk_bf16_f32 v94, v94, v95
	v_cvt_pk_bf16_f32 v95, v96, v97
	v_cvt_pk_bf16_f32 v90, v90, v91
	v_cvt_pk_bf16_f32 v91, v92, v93
	v_cvt_pk_bf16_f32 v86, v86, v87
	v_cvt_pk_bf16_f32 v87, v88, v89
	v_cvt_pk_bf16_f32 v82, v82, v83
	v_cvt_pk_bf16_f32 v83, v84, v85
	global_store_dwordx2 v[148:149], v[94:95], off
	global_store_dwordx2 v[148:149], v[90:91], off offset:32
	global_store_dwordx2 v[148:149], v[86:87], off offset:256
	global_store_dwordx2 v[148:149], v[82:83], off offset:288
	v_add_u32_e32 v134, 0x4000, v134
	v_lshl_add_u64 v[148:149], s[44:45], 0, v[134:135]
	v_cvt_pk_bf16_f32 v78, v78, v79
	v_cvt_pk_bf16_f32 v79, v80, v81
	v_cvt_pk_bf16_f32 v74, v74, v75
	v_cvt_pk_bf16_f32 v75, v76, v77
	v_cvt_pk_bf16_f32 v70, v70, v71
	v_cvt_pk_bf16_f32 v71, v72, v73
	v_cvt_pk_bf16_f32 v66, v66, v67
	v_cvt_pk_bf16_f32 v67, v68, v69
	global_store_dwordx2 v[148:149], v[78:79], off
	global_store_dwordx2 v[148:149], v[74:75], off offset:32
	global_store_dwordx2 v[148:149], v[70:71], off offset:256
	global_store_dwordx2 v[148:149], v[66:67], off offset:288
	v_add_u32_e32 v134, 0x14000, v134
	v_lshl_add_u64 v[148:149], s[44:45], 0, v[134:135]
	v_cvt_pk_bf16_f32 v62, v62, v63
	v_cvt_pk_bf16_f32 v63, v64, v65
	v_cvt_pk_bf16_f32 v58, v58, v59
	v_cvt_pk_bf16_f32 v59, v60, v61
	v_cvt_pk_bf16_f32 v54, v54, v55
	v_cvt_pk_bf16_f32 v55, v56, v57
	v_cvt_pk_bf16_f32 v50, v50, v51
	v_cvt_pk_bf16_f32 v51, v52, v53
	global_store_dwordx2 v[148:149], v[62:63], off
	global_store_dwordx2 v[148:149], v[58:59], off offset:32
	global_store_dwordx2 v[148:149], v[54:55], off offset:256
	global_store_dwordx2 v[148:149], v[50:51], off offset:288
	v_add_u32_e32 v134, 0x4000, v134
	v_lshl_add_u64 v[148:149], s[44:45], 0, v[134:135]
	v_cvt_pk_bf16_f32 v46, v46, v47
	v_cvt_pk_bf16_f32 v47, v48, v49
	v_cvt_pk_bf16_f32 v42, v42, v43
	v_cvt_pk_bf16_f32 v43, v44, v45
	v_cvt_pk_bf16_f32 v38, v38, v39
	v_cvt_pk_bf16_f32 v39, v40, v41
	v_cvt_pk_bf16_f32 v34, v34, v35
	v_cvt_pk_bf16_f32 v35, v36, v37
	global_store_dwordx2 v[148:149], v[46:47], off
	global_store_dwordx2 v[148:149], v[42:43], off offset:32
	global_store_dwordx2 v[148:149], v[38:39], off offset:256
	global_store_dwordx2 v[148:149], v[34:35], off offset:288
	v_add_u32_e32 v134, 0x4000, v134
	v_lshl_add_u64 v[148:149], s[44:45], 0, v[134:135]
	v_cvt_pk_bf16_f32 v30, v30, v31
	v_cvt_pk_bf16_f32 v31, v32, v33
	v_cvt_pk_bf16_f32 v26, v26, v27
	v_cvt_pk_bf16_f32 v27, v28, v29
	v_cvt_pk_bf16_f32 v22, v22, v23
	v_cvt_pk_bf16_f32 v23, v24, v25
	v_cvt_pk_bf16_f32 v18, v18, v19
	v_cvt_pk_bf16_f32 v19, v20, v21
	global_store_dwordx2 v[148:149], v[30:31], off
	global_store_dwordx2 v[148:149], v[26:27], off offset:32
	global_store_dwordx2 v[148:149], v[22:23], off offset:256
	global_store_dwordx2 v[148:149], v[18:19], off offset:288
	v_add_u32_e32 v134, 0x4000, v134
	v_lshl_add_u64 v[148:149], s[44:45], 0, v[134:135]
	v_add_u32_e32 v145, 0xb0, v146
	v_and_b32_e32 v152, 0xfff, v145
	v_cmp_lt_u32_e32 vcc, 0xff0, v152
	s_and_saveexec_b64 s[2:3], vcc
	s_cbranch_execz .Lp1e_u_skip
	v_lshrrev_b32_e32 v145, 12, v145
	v_mul_u32_u24_e32 v145, 15, v145
	v_add_u32_e32 v145, v145, v152
	v_add_u32_e32 v145, 0xfffff00f, v145
	v_lshl_add_u32 v152, v145, 11, v147
	v_add_u32_e32 v152, 0x8100000, v152
	v_lshl_add_u64 v[150:151], s[84:85], 0, v[152:153]
	global_store_dwordx4 v[150:151], v[14:17], off
	global_store_dwordx4 v[150:151], v[10:13], off offset:64
	global_store_dwordx4 v[150:151], v[6:9], off offset:512
	global_store_dwordx4 v[150:151], v[2:5], off offset:576
.Lp1e_u_skip:
	s_or_b64 exec, exec, s[2:3]
	v_cvt_pk_bf16_f32 v14, v14, v15
	v_cvt_pk_bf16_f32 v15, v16, v17
	v_cvt_pk_bf16_f32 v10, v10, v11
	v_cvt_pk_bf16_f32 v11, v12, v13
	v_cvt_pk_bf16_f32 v6, v6, v7
	v_cvt_pk_bf16_f32 v7, v8, v9
	v_cvt_pk_bf16_f32 v2, v2, v3
	v_cvt_pk_bf16_f32 v3, v4, v5
	global_store_dwordx2 v[148:149], v[14:15], off
	global_store_dwordx2 v[148:149], v[10:11], off offset:32
	global_store_dwordx2 v[148:149], v[6:7], off offset:256
	global_store_dwordx2 v[148:149], v[2:3], off offset:288
	s_branch .LBB0_223
